# scan pass B early decay section: the four log-f TRR reads issued together; later waits counted so they skip the q/k ds_read_b64 pairs
# baseline (speedup 1.0000x reference)
.LBB0_606:
	s_mov_b32 s0, s94
	s_add_i32 s94, s94, 1
	s_lshl_b32 s1, s94, 6
	s_cmp_lg_u32 s0, 15
	s_cselect_b32 s0, s1, 0x3c0
	s_add_u32 s0, s48, s0
	v_mov_b32_e32 v128, v165
	v_mov_b32_e32 v187, v166
	s_addc_u32 s1, s49, 0
	v_mov_b32_e32 v44, v164
	s_waitcnt lgkmcnt(0)
	s_barrier
	s_lshl_b64 s[0:1], s[0:1], 11
	v_lshlrev_b32_e32 v45, 6, v44
	v_lshlrev_b32_e32 v44, 3, v44
	s_add_u32 s30, s70, s0
	v_and_b32_e32 v45, 0xfffffc00, v45
	v_and_b32_e32 v44, 0x78, v44
	s_addc_u32 s31, s71, s1
	v_or3_b32 v172, v45, v44, s93
	s_add_u32 s36, s80, s0
	s_addc_u32 s37, s81, s1
	v_lshlrev_b64 v[56:57], 1, v[172:173]
	v_lshl_add_u64 v[48:49], s[30:31], 0, v[56:57]
	v_lshl_add_u64 v[58:59], s[36:37], 0, v[56:57]
	global_load_dwordx4 v[44:47], v[48:49], off
	global_load_dwordx4 v[52:55], v[58:59], off
	v_add_co_u32_e32 v48, vcc, s21, v48
	s_add_u32 s0, s72, s0
	s_nop 0
	v_addc_co_u32_e32 v49, vcc, 0, v49, vcc
	v_lshlrev_b32_e32 v68, 2, v128
	s_addc_u32 s1, s73, s1
	v_add_co_u32_e32 v58, vcc, s21, v58
	v_ashrrev_i32_e32 v188, 2, v128
	v_and_b32_e32 v189, 12, v68
	v_addc_co_u32_e32 v59, vcc, 0, v59, vcc
	v_lshl_add_u64 v[60:61], s[0:1], 0, v[56:57]
	v_lshl_add_u32 v73, v187, 3, v188
	v_or_b32_e32 v68, s42, v189
	v_lshlrev_b32_e32 v130, 2, v187
	global_load_dwordx4 v[48:51], v[48:49], off
	v_lshl_add_u32 v72, v68, 1, s64
	global_load_dwordx4 v[64:67], v[58:59], off
	v_sub_u32_e32 v190, v73, v130
	global_load_dwordx4 v[56:59], v[60:61], off
	v_add_co_u32_e32 v60, vcc, s21, v60
	v_mad_u64_u32 v[74:75], s[0:1], v73, s61, v[72:73]
	s_nop 0
	v_addc_co_u32_e32 v61, vcc, 0, v61, vcc
	v_mad_u64_u32 v[72:73], s[0:1], v190, s61, v[72:73]
	global_load_dwordx4 v[60:63], v[60:61], off
	ds_read_b64_tr_b16 v[68:69], v74
	ds_read_b64_tr_b16 v[70:71], v74 offset:1088
	ds_read_b64_tr_b16 v[76:77], v74 offset:8704
	ds_read_b64_tr_b16 v[78:79], v74 offset:9792
	ds_read_b64_tr_b16 v[74:75], v72
	ds_read_b64_tr_b16 v[240:241], v72 offset:4352
	ds_read_b64_tr_b16 v[242:243], v72 offset:8704
	ds_read_b64_tr_b16 v[244:245], v72 offset:13056
	v_lshlrev_b32_e32 v82, 1, v128
	v_add_u32_e32 v80, s42, v130
	v_lshlrev_b32_e32 v172, 1, v80
	v_mul_lo_u32 v185, v128, s61
	s_waitcnt lgkmcnt(0)
	v_lshlrev_b32_e32 v73, 16, v74
	v_mul_f32_e32 v73, 0x3fb8aa3b, v73
	v_exp_f32_e32 v150, v73
	v_and_b32_e32 v73, 0xffff0000, v74
	v_mul_f32_e32 v73, 0x3fb8aa3b, v73
	v_exp_f32_e32 v151, v73
	v_lshlrev_b32_e32 v73, 16, v75
	v_mul_f32_e32 v73, 0x3fb8aa3b, v73
	v_exp_f32_e32 v148, v73
	v_and_b32_e32 v73, 0xffff0000, v75
	v_mul_f32_e32 v73, 0x3fb8aa3b, v73
	v_exp_f32_e32 v149, v73
	v_and_b32_e32 v73, 0x70, v82
	v_add_lshl_u32 v73, v73, v80, 1
	v_and_b32_e32 v73, 0xf8, v73
	v_add_u32_e32 v81, s64, v172
	v_add3_u32 v73, s66, v185, v73
	ds_read_b64 v[146:147], v73
	v_add_u32_e32 v73, v81, v185
	ds_read_b64 v[140:141], v73
	v_add_u32_e32 v129, 0x1100, v185
	v_add_u32_e32 v186, 0x2200, v185
	v_add_u32_e32 v131, 0x3300, v185
	v_mfma_f32_16x16x32_bf16 v[192:195], v[4:7], v[68:71], 0
	s_waitcnt lgkmcnt(2)
	v_lshlrev_b32_e32 v73, 16, v240
	v_mul_f32_e32 v73, 0x3fb8aa3b, v73
	v_exp_f32_e32 v154, v73
	v_and_b32_e32 v73, 0xffff0000, v240
	v_mul_f32_e32 v73, 0x3fb8aa3b, v73
	v_exp_f32_e32 v155, v73
	v_lshlrev_b32_e32 v73, 16, v241
	v_mul_f32_e32 v73, 0x3fb8aa3b, v73
	v_exp_f32_e32 v152, v73
	v_and_b32_e32 v73, 0xffff0000, v241
	v_mul_f32_e32 v73, 0x3fb8aa3b, v73
	v_exp_f32_e32 v153, v73
	v_add_u32_e32 v73, 32, v82
	v_and_b32_e32 v73, 0x70, v73
	v_add_lshl_u32 v73, v73, v80, 1
	v_and_b32_e32 v73, 0xf8, v73
	v_add3_u32 v73, s66, v129, v73
	ds_read_b64 v[142:143], v73
	v_add_u32_e32 v73, v81, v129
	ds_read_b64 v[136:137], v73
	v_mfma_f32_16x16x32_bf16 v[196:199], v[0:3], v[68:71], 0
	v_add_f32_e64 v148, -v148, 1.0
	v_add_f32_e64 v149, -v149, 1.0
	s_andn2_b64 vcc, exec, s[34:35]
	s_mov_b64 s[30:31], s[18:19]
	s_waitcnt lgkmcnt(4)
	v_lshlrev_b32_e32 v73, 16, v242
	v_mul_f32_e32 v73, 0x3fb8aa3b, v73
	v_exp_f32_e32 v158, v73
	v_and_b32_e32 v73, 0xffff0000, v242
	v_mul_f32_e32 v73, 0x3fb8aa3b, v73
	v_exp_f32_e32 v159, v73
	v_lshlrev_b32_e32 v73, 16, v243
	v_mul_f32_e32 v73, 0x3fb8aa3b, v73
	v_exp_f32_e32 v156, v73
	v_and_b32_e32 v73, 0xffff0000, v243
	v_mul_f32_e32 v73, 0x3fb8aa3b, v73
	v_exp_f32_e32 v157, v73
	v_add_u32_e32 v73, 64, v82
	v_and_b32_e32 v73, 0x70, v73
	v_add_lshl_u32 v73, v73, v80, 1
	v_and_b32_e32 v73, 0xf8, v73
	v_add3_u32 v73, s66, v186, v73
	ds_read_b64 v[134:135], v73
	v_add_u32_e32 v73, v81, v186
	ds_read_b64 v[144:145], v73
	v_mfma_f32_16x16x32_bf16 v[96:99], v[68:71], v[4:7], 0
	s_waitcnt lgkmcnt(6)
	v_lshlrev_b32_e32 v74, 16, v244
	v_and_b32_e32 v72, 0xffff0000, v244
	v_mul_f32_e32 v72, 0x3fb8aa3b, v72
	v_exp_f32_e32 v163, v72
	v_lshlrev_b32_e32 v72, 16, v245
	v_mul_f32_e32 v72, 0x3fb8aa3b, v72
	v_exp_f32_e32 v160, v72
	v_and_b32_e32 v72, 0xffff0000, v245
	v_mul_f32_e32 v72, 0x3fb8aa3b, v72
	v_exp_f32_e32 v161, v72
	v_add_u32_e32 v72, 0x60, v82
	v_and_b32_e32 v72, 0x70, v72
	v_add_lshl_u32 v72, v72, v80, 1
	v_and_b32_e32 v72, 0xf8, v72
	v_add3_u32 v72, s66, v131, v72
	v_mul_f32_e32 v74, 0x3fb8aa3b, v74
	s_waitcnt lgkmcnt(0)
	ds_read_b64 v[132:133], v72
	v_add_u32_e32 v72, v81, v131
	v_exp_f32_e32 v162, v74
	ds_read_b64 v[138:139], v72
	v_mov_b64_e32 v[74:75], s[46:47]
	v_mov_b64_e32 v[72:73], s[44:45]
	v_mfma_f32_16x16x32_bf16 v[88:91], v[68:71], v[0:3], 0
	s_nop 0
	v_mfma_f32_16x16x32_bf16 v[80:83], v[72:75], v[68:71], 0
	v_mfma_f32_16x16x32_bf16 v[220:223], v[72:75], v[76:79], v[80:83]
	v_mfma_f32_16x16x32_bf16 v[224:227], v[68:71], v[72:75], 0
	v_mfma_f32_16x16x32_bf16 v[92:95], v[68:71], v[8:11], 0
	s_nop 5
	v_sub_f32_e32 v68, v220, v192
	v_sub_f32_e32 v69, v221, v193
	v_mul_f32_e32 v68, 0x3fb8aa3b, v68
	v_mul_f32_e32 v69, 0x3fb8aa3b, v69
	v_exp_f32_e32 v68, v68
	v_exp_f32_e32 v69, v69
	v_pk_add_f32 v[70:71], v[150:151], 1.0 op_sel_hi:[1,0] neg_lo:[1,0] neg_hi:[1,0]
	v_pk_add_f32 v[150:151], v[154:155], 1.0 op_sel_hi:[1,0] neg_lo:[1,0] neg_hi:[1,0]
	v_mfma_f32_16x16x32_bf16 v[200:203], v[4:7], v[76:79], v[80:83]
	v_mul_f32_e64 v68, v70, v68
	v_mul_f32_e64 v69, v71, v69
	v_sub_f32_e32 v70, v222, v194
	v_sub_f32_e32 v71, v223, v195
	v_mul_f32_e32 v70, 0x3fb8aa3b, v70
	v_mul_f32_e32 v71, 0x3fb8aa3b, v71
	v_exp_f32_e32 v70, v70
	v_exp_f32_e32 v71, v71
	v_mfma_f32_16x16x32_bf16 v[204:207], v[0:3], v[76:79], v[80:83]
	v_sub_f32_e32 v96, v96, v92
	v_sub_f32_e32 v97, v97, v93
	v_pk_mul_f32 v[70:71], v[148:149], v[70:71]
	v_sub_f32_e32 v148, v220, v196
	v_sub_f32_e32 v149, v221, v197
	v_mul_f32_e32 v148, 0x3fb8aa3b, v148
	v_mul_f32_e32 v149, 0x3fb8aa3b, v149
	v_exp_f32_e32 v148, v148
	v_exp_f32_e32 v149, v149
	v_mfma_f32_16x16x32_bf16 v[84:87], v[76:79], v[4:7], v[224:227]
	v_sub_f32_e32 v98, v98, v94
	v_sub_f32_e32 v99, v99, v95
	v_pk_mul_f32 v[154:155], v[150:151], v[148:149]
	v_sub_f32_e32 v148, v222, v198
	v_sub_f32_e32 v149, v223, v199
	v_mul_f32_e32 v148, 0x3fb8aa3b, v148
	v_mul_f32_e32 v149, 0x3fb8aa3b, v149
	v_exp_f32_e32 v148, v148
	v_exp_f32_e32 v149, v149
	v_pk_add_f32 v[150:151], v[152:153], 1.0 op_sel_hi:[1,0] neg_lo:[1,0] neg_hi:[1,0]
	v_mfma_f32_16x16x32_bf16 v[80:83], v[76:79], v[0:3], v[224:227]
	v_med3_f32 v191, v96, s67, v218
	v_pk_mul_f32 v[152:153], v[150:151], v[148:149]
	v_sub_f32_e32 v148, v220, v200
	v_sub_f32_e32 v149, v221, v201
	v_mul_f32_e32 v148, 0x3fb8aa3b, v148
	v_mul_f32_e32 v149, 0x3fb8aa3b, v149
	v_exp_f32_e32 v148, v148
	v_exp_f32_e32 v149, v149
	v_pk_add_f32 v[150:151], v[158:159], 1.0 op_sel_hi:[1,0] neg_lo:[1,0] neg_hi:[1,0]
	v_med3_f32 v194, v97, s67, v218
	v_med3_f32 v195, v98, s67, v218
	v_pk_mul_f32 v[158:159], v[150:151], v[148:149]
	v_sub_f32_e32 v148, v222, v202
	v_sub_f32_e32 v149, v223, v203
	v_mul_f32_e32 v148, 0x3fb8aa3b, v148
	v_mul_f32_e32 v149, 0x3fb8aa3b, v149
	v_exp_f32_e32 v148, v148
	v_exp_f32_e32 v149, v149
	v_pk_add_f32 v[150:151], v[156:157], 1.0 op_sel_hi:[1,0] neg_lo:[1,0] neg_hi:[1,0]
	v_med3_f32 v196, v99, s67, v218
	v_mul_f32_e32 v96, 0x3fb8aa3b, v191
	v_pk_mul_f32 v[156:157], v[150:151], v[148:149]
	v_sub_f32_e32 v148, v220, v204
	v_sub_f32_e32 v149, v221, v205
	v_mul_f32_e32 v148, 0x3fb8aa3b, v148
	v_mul_f32_e32 v149, 0x3fb8aa3b, v149
	v_exp_f32_e32 v148, v148
	v_exp_f32_e32 v149, v149
	v_pk_add_f32 v[150:151], v[162:163], 1.0 op_sel_hi:[1,0] neg_lo:[1,0] neg_hi:[1,0]
	v_mul_f32_e32 v97, 0x3fb8aa3b, v194
	v_mul_f32_e32 v98, 0x3fb8aa3b, v195
	v_pk_mul_f32 v[162:163], v[150:151], v[148:149]
	v_sub_f32_e32 v148, v222, v206
	v_mul_f32_e32 v148, 0x3fb8aa3b, v148
	v_exp_f32_e32 v192, v148
	v_sub_f32_e32 v148, v223, v207
	v_mul_f32_e32 v148, 0x3fb8aa3b, v148
	v_exp_f32_e32 v193, v148
	v_mfma_f32_16x16x32_bf16 v[148:151], v[76:79], v[72:75], v[224:227]
	v_cvt_pk_bf16_f32 v75, v152, v153
	v_pk_add_f32 v[152:153], v[160:161], 1.0 op_sel_hi:[1,0] neg_lo:[1,0] neg_hi:[1,0]
	v_cvt_pk_bf16_f32 v73, v70, v71
	v_mfma_f32_16x16x32_bf16 v[76:79], v[76:79], v[8:11], v[224:227]
	v_mul_f32_e64 v152, v152, v192
	v_mul_f32_e64 v153, v153, v193
	v_cvt_pk_bf16_f32 v74, v154, v155
	v_cvt_pk_bf16_f32 v71, v152, v153
	v_mul_f32_e32 v152, 0x3fb8aa3b, v92
	v_exp_f32_e32 v160, v152
	s_nop 1
	v_mul_f32_e32 v152, 0x3fb8aa3b, v76
	v_exp_f32_e32 v154, v152
	v_sub_f32_e32 v152, v76, v92
	v_mul_f32_e32 v152, 0x3fb8aa3b, v152
	v_cvt_pk_bf16_f32 v72, v68, v69
	v_cvt_pk_bf16_f32 v69, v156, v157
	v_exp_f32_e32 v156, v152
	v_mul_f32_e32 v152, 0x3fb8aa3b, v93
	v_exp_f32_e32 v161, v152
	v_mul_f32_e32 v152, 0x3fb8aa3b, v77
	v_exp_f32_e32 v155, v152
	v_sub_f32_e32 v152, v77, v93
	v_sub_f32_e32 v153, v78, v94
	v_mul_f32_e32 v152, 0x3fb8aa3b, v152
	v_mul_f32_e32 v153, 0x3fb8aa3b, v153
	v_mul_f32_e32 v99, 0x3fb8aa3b, v196
	v_cvt_pk_bf16_f32 v68, v158, v159
	v_exp_f32_e32 v157, v152
	v_mul_f32_e32 v152, 0x3fb8aa3b, v94
	v_exp_f32_e32 v158, v153
	v_mul_f32_e32 v153, 0x3fb8aa3b, v95
	v_exp_f32_e32 v96, v96
	v_exp_f32_e32 v97, v97
	v_exp_f32_e32 v98, v98
	v_exp_f32_e32 v99, v99
	v_cvt_pk_bf16_f32 v70, v162, v163
	v_exp_f32_e32 v162, v152
	v_exp_f32_e32 v163, v153
	v_lshlrev_b32_e32 v192, 16, v146
	v_and_b32_e32 v193, 0xffff0000, v146
	v_lshlrev_b32_e32 v146, 16, v147
	v_and_b32_e32 v147, 0xffff0000, v147
	v_pk_mul_f32 v[96:97], v[96:97], v[192:193]
	v_pk_mul_f32 v[98:99], v[98:99], v[146:147]
	v_pk_mul_f32 v[192:193], v[160:161], v[96:97]
	v_pk_mul_f32 v[146:147], v[162:163], v[98:99]
	v_cvt_pk_bf16_f32 v192, v192, v193
	v_cvt_pk_bf16_f32 v193, v146, v147
	v_cvt_pk_bf16_f32 v96, v96, v97
	v_cvt_pk_bf16_f32 v97, v98, v99
	v_add3_u32 v197, v172, v185, 0
	ds_write2st64_b64 v197, v[192:193], v[96:97] offset1:34
	v_mul_f32_e32 v97, 0xbfb8aa3b, v191
	v_lshlrev_b32_e32 v96, 16, v140
	v_exp_f32_e32 v98, v97
	v_and_b32_e32 v97, 0xffff0000, v140
	v_mul_f32_e32 v96, 0x3fb8aa3b, v96
	v_mul_f32_e32 v97, 0x3fb8aa3b, v97
	v_exp_f32_e32 v96, v96
	v_exp_f32_e32 v97, v97
	v_mul_f32_e32 v99, 0xbfb8aa3b, v194
	v_exp_f32_e32 v99, v99
	v_sub_f32_e32 v159, v79, v95
	v_pk_add_f32 v[96:97], v[96:97], 1.0 op_sel_hi:[1,0] neg_lo:[1,0] neg_hi:[1,0]
	v_mul_f32_e32 v159, 0x3fb8aa3b, v159
	v_pk_mul_f32 v[96:97], v[96:97], v[98:99]
	v_lshlrev_b32_e32 v99, 16, v141
	v_mul_f32_e32 v99, 0x3fb8aa3b, v99
	v_exp_f32_e32 v140, v99
	v_mul_f32_e32 v99, 0xbfb8aa3b, v195
	v_exp_f32_e32 v146, v99
	v_and_b32_e32 v99, 0xffff0000, v141
	v_mul_f32_e32 v99, 0x3fb8aa3b, v99
	v_exp_f32_e32 v141, v99
	v_mul_f32_e32 v99, 0xbfb8aa3b, v196
	v_exp_f32_e32 v147, v99
	v_exp_f32_e32 v159, v159
	v_pk_add_f32 v[140:141], v[140:141], 1.0 op_sel_hi:[1,0] neg_lo:[1,0] neg_hi:[1,0]
	v_cvt_pk_bf16_f32 v98, v96, v97
	v_pk_mul_f32 v[140:141], v[140:141], v[146:147]
	v_pk_mul_f32 v[96:97], v[156:157], v[96:97]
	v_cvt_pk_bf16_f32 v99, v140, v141
	v_pk_mul_f32 v[140:141], v[158:159], v[140:141]
	v_cvt_pk_bf16_f32 v96, v96, v97
	v_cvt_pk_bf16_f32 v97, v140, v141
	v_sub_f32_e32 v88, v88, v92
	v_sub_f32_e32 v89, v89, v93
	v_sub_f32_e32 v90, v90, v94
	v_sub_f32_e32 v91, v91, v95
	ds_write2st64_b64 v197, v[98:99], v[96:97] offset0:68 offset1:85
	v_med3_f32 v96, v88, s67, v218
	v_med3_f32 v97, v89, s67, v218
	v_med3_f32 v98, v90, s67, v218
	v_med3_f32 v99, v91, s67, v218
	v_mul_f32_e32 v88, 0x3fb8aa3b, v96
	v_mul_f32_e32 v89, 0x3fb8aa3b, v97
	v_mul_f32_e32 v90, 0x3fb8aa3b, v98
	v_mul_f32_e32 v91, 0x3fb8aa3b, v99
	v_exp_f32_e32 v88, v88
	v_exp_f32_e32 v89, v89
	v_exp_f32_e32 v90, v90
	v_exp_f32_e32 v91, v91
	v_lshlrev_b32_e32 v92, 16, v142
	v_and_b32_e32 v93, 0xffff0000, v142
	v_lshlrev_b32_e32 v94, 16, v143
	v_and_b32_e32 v95, 0xffff0000, v143
	v_pk_mul_f32 v[88:89], v[88:89], v[92:93]
	v_pk_mul_f32 v[90:91], v[90:91], v[94:95]
	v_pk_mul_f32 v[92:93], v[160:161], v[88:89]
	v_pk_mul_f32 v[94:95], v[162:163], v[90:91]
	v_cvt_pk_bf16_f32 v92, v92, v93
	v_cvt_pk_bf16_f32 v93, v94, v95
	v_cvt_pk_bf16_f32 v88, v88, v89
	v_cvt_pk_bf16_f32 v89, v90, v91
	v_add3_u32 v140, v172, v129, 0
	ds_write2st64_b64 v140, v[92:93], v[88:89] offset1:34
	v_mul_f32_e32 v89, 0xbfb8aa3b, v96
	v_lshlrev_b32_e32 v88, 16, v136
	v_exp_f32_e32 v90, v89
	v_and_b32_e32 v89, 0xffff0000, v136
	v_mul_f32_e32 v88, 0x3fb8aa3b, v88
	v_mul_f32_e32 v89, 0x3fb8aa3b, v89
	v_exp_f32_e32 v88, v88
	v_exp_f32_e32 v89, v89
	v_mul_f32_e32 v91, 0xbfb8aa3b, v97
	v_exp_f32_e32 v91, v91
	v_sub_f32_e32 v84, v84, v76
	v_pk_add_f32 v[88:89], v[88:89], 1.0 op_sel_hi:[1,0] neg_lo:[1,0] neg_hi:[1,0]
	v_sub_f32_e32 v85, v85, v77
	v_pk_mul_f32 v[88:89], v[88:89], v[90:91]
	v_lshlrev_b32_e32 v91, 16, v137
	v_mul_f32_e32 v91, 0x3fb8aa3b, v91
	v_exp_f32_e32 v92, v91
	v_mul_f32_e32 v91, 0xbfb8aa3b, v98
	v_exp_f32_e32 v94, v91
	v_and_b32_e32 v91, 0xffff0000, v137
	v_mul_f32_e32 v91, 0x3fb8aa3b, v91
	v_exp_f32_e32 v93, v91
	v_mul_f32_e32 v91, 0xbfb8aa3b, v99
	v_exp_f32_e32 v95, v91
	v_cvt_pk_bf16_f32 v90, v88, v89
	v_pk_add_f32 v[92:93], v[92:93], 1.0 op_sel_hi:[1,0] neg_lo:[1,0] neg_hi:[1,0]
	v_pk_mul_f32 v[88:89], v[156:157], v[88:89]
	v_pk_mul_f32 v[92:93], v[92:93], v[94:95]
	v_cvt_pk_bf16_f32 v88, v88, v89
	v_cvt_pk_bf16_f32 v91, v92, v93
	v_pk_mul_f32 v[92:93], v[158:159], v[92:93]
	v_sub_f32_e32 v86, v86, v78
	v_cvt_pk_bf16_f32 v89, v92, v93
	ds_write2st64_b64 v140, v[90:91], v[88:89] offset0:68 offset1:85
	v_lshlrev_b32_e32 v88, 16, v144
	v_and_b32_e32 v89, 0xffff0000, v144
	v_mul_f32_e32 v88, 0x3fb8aa3b, v88
	v_mul_f32_e32 v89, 0x3fb8aa3b, v89
	v_med3_f32 v92, v84, s67, v218
	v_med3_f32 v93, v85, s67, v218
	v_exp_f32_e32 v88, v88
	v_exp_f32_e32 v89, v89
	v_mul_f32_e32 v84, 0x3fb8aa3b, v92
	v_mul_f32_e32 v92, 0xbfb8aa3b, v92
	v_mul_f32_e32 v85, 0x3fb8aa3b, v93
	v_mul_f32_e32 v93, 0xbfb8aa3b, v93
	v_exp_f32_e32 v92, v92
	v_exp_f32_e32 v93, v93
	v_pk_add_f32 v[88:89], v[88:89], 1.0 op_sel_hi:[1,0] neg_lo:[1,0] neg_hi:[1,0]
	v_sub_f32_e32 v87, v87, v79
	v_lshlrev_b32_e32 v90, 16, v145
	v_pk_mul_f32 v[88:89], v[88:89], v[92:93]
	v_med3_f32 v92, v86, s67, v218
	v_med3_f32 v93, v87, s67, v218
	v_and_b32_e32 v91, 0xffff0000, v145
	v_mul_f32_e32 v86, 0x3fb8aa3b, v92
	v_mul_f32_e32 v87, 0x3fb8aa3b, v93
	v_mul_f32_e32 v152, 0x3fb8aa3b, v78
	v_mul_f32_e32 v153, 0x3fb8aa3b, v79
	v_mul_f32_e32 v90, 0x3fb8aa3b, v90
	v_mul_f32_e32 v91, 0x3fb8aa3b, v91
	v_exp_f32_e32 v84, v84
	v_exp_f32_e32 v85, v85
	v_exp_f32_e32 v86, v86
	v_exp_f32_e32 v87, v87
	v_exp_f32_e32 v152, v152
	v_exp_f32_e32 v153, v153
	v_exp_f32_e32 v90, v90
	v_exp_f32_e32 v91, v91
	v_mul_f32_e32 v92, 0xbfb8aa3b, v92
	v_mul_f32_e32 v93, 0xbfb8aa3b, v93
	v_exp_f32_e32 v92, v92
	v_exp_f32_e32 v93, v93
	v_lshlrev_b32_e32 v94, 16, v134
	v_and_b32_e32 v95, 0xffff0000, v134
	v_lshlrev_b32_e32 v96, 16, v135
	v_and_b32_e32 v97, 0xffff0000, v135
	v_pk_mul_f32 v[84:85], v[84:85], v[94:95]
	v_pk_mul_f32 v[86:87], v[86:87], v[96:97]
	v_pk_mul_f32 v[94:95], v[154:155], v[84:85]
	v_pk_mul_f32 v[96:97], v[152:153], v[86:87]
	v_pk_add_f32 v[90:91], v[90:91], 1.0 op_sel_hi:[1,0] neg_lo:[1,0] neg_hi:[1,0]
	v_cvt_pk_bf16_f32 v84, v84, v85
	v_pk_mul_f32 v[90:91], v[90:91], v[92:93]
	v_cvt_pk_bf16_f32 v92, v94, v95
	v_cvt_pk_bf16_f32 v93, v96, v97
	v_cvt_pk_bf16_f32 v85, v86, v87
	v_cvt_pk_bf16_f32 v86, v88, v89
	v_add3_u32 v88, v172, v186, 0
	v_cvt_pk_bf16_f32 v87, v90, v91
	ds_write2st64_b64 v88, v[92:93], v[84:85] offset1:34
	ds_write_b64 v88, v[86:87] offset:43520
	s_waitcnt lgkmcnt(6)
	v_lshlrev_b32_e32 v84, 16, v138
	v_and_b32_e32 v85, 0xffff0000, v138
	v_sub_f32_e32 v76, v80, v76
	v_sub_f32_e32 v77, v81, v77
	v_mul_f32_e32 v84, 0x3fb8aa3b, v84
	v_mul_f32_e32 v85, 0x3fb8aa3b, v85
	v_med3_f32 v80, v76, s67, v218
	v_med3_f32 v81, v77, s67, v218
	v_sub_f32_e32 v78, v82, v78
	v_sub_f32_e32 v79, v83, v79
	v_exp_f32_e32 v84, v84
	v_exp_f32_e32 v85, v85
	v_mul_f32_e32 v76, 0x3fb8aa3b, v80
	v_mul_f32_e32 v80, 0xbfb8aa3b, v80
	v_mul_f32_e32 v77, 0x3fb8aa3b, v81
	v_mul_f32_e32 v81, 0xbfb8aa3b, v81
	v_med3_f32 v82, v78, s67, v218
	v_med3_f32 v83, v79, s67, v218
	v_lshlrev_b32_e32 v86, 16, v139
	v_and_b32_e32 v87, 0xffff0000, v139
	v_exp_f32_e32 v80, v80
	v_exp_f32_e32 v81, v81
	v_mul_f32_e32 v78, 0x3fb8aa3b, v82
	v_mul_f32_e32 v79, 0x3fb8aa3b, v83
	v_mul_f32_e32 v86, 0x3fb8aa3b, v86
	v_mul_f32_e32 v87, 0x3fb8aa3b, v87
	v_exp_f32_e32 v76, v76
	v_exp_f32_e32 v77, v77
	v_exp_f32_e32 v78, v78
	v_exp_f32_e32 v79, v79
	v_exp_f32_e32 v86, v86
	v_exp_f32_e32 v87, v87
	v_mul_f32_e32 v82, 0xbfb8aa3b, v82
	v_mul_f32_e32 v83, 0xbfb8aa3b, v83
	v_pk_add_f32 v[84:85], v[84:85], 1.0 op_sel_hi:[1,0] neg_lo:[1,0] neg_hi:[1,0]
	v_exp_f32_e32 v82, v82
	v_exp_f32_e32 v83, v83
	v_lshlrev_b32_e32 v88, 16, v132
	v_and_b32_e32 v89, 0xffff0000, v132
	v_pk_mul_f32 v[80:81], v[84:85], v[80:81]
	v_lshlrev_b32_e32 v84, 16, v133
	v_and_b32_e32 v85, 0xffff0000, v133
	v_pk_mul_f32 v[76:77], v[76:77], v[88:89]
	v_pk_mul_f32 v[78:79], v[78:79], v[84:85]
	v_pk_mul_f32 v[88:89], v[154:155], v[76:77]
	v_pk_mul_f32 v[84:85], v[152:153], v[78:79]
	v_pk_add_f32 v[86:87], v[86:87], 1.0 op_sel_hi:[1,0] neg_lo:[1,0] neg_hi:[1,0]
	v_cvt_pk_bf16_f32 v76, v76, v77
	v_pk_mul_f32 v[82:83], v[86:87], v[82:83]
	v_cvt_pk_bf16_f32 v86, v88, v89
	v_cvt_pk_bf16_f32 v87, v84, v85
	v_cvt_pk_bf16_f32 v77, v78, v79
	v_cvt_pk_bf16_f32 v78, v80, v81
	v_add3_u32 v80, v172, v131, 0
	v_cvt_pk_bf16_f32 v79, v82, v83
	ds_write2st64_b64 v80, v[86:87], v[76:77] offset1:34
	ds_write_b64 v80, v[78:79] offset:43520
	v_lshlrev_b32_e32 v92, 1, v189
	v_mul_lo_u32 v76, v190, s20
	v_mul_f32_e32 v148, 0x3fb8aa3b, v148
	v_mul_f32_e32 v149, 0x3fb8aa3b, v149
	v_mul_f32_e32 v150, 0x3fb8aa3b, v150
	v_mul_f32_e32 v151, 0x3fb8aa3b, v151
	s_waitcnt lgkmcnt(0)
	s_barrier
	v_add3_u32 v84, s60, v92, v76
	v_exp_f32_e32 v148, v148
	v_exp_f32_e32 v149, v149
	v_exp_f32_e32 v150, v150
	v_exp_f32_e32 v151, v151
	ds_read_b64_tr_b16 v[76:77], v84
	ds_read_b64_tr_b16 v[80:81], v84 offset:32
	ds_read_b64_tr_b16 v[78:79], v84 offset:4608
	v_pk_mul_f32 v[12:13], v[12:13], v[148:149]
	v_pk_mul_f32 v[16:17], v[16:17], v[148:149]
	v_pk_mul_f32 v[14:15], v[14:15], v[150:151]
	v_pk_mul_f32 v[18:19], v[18:19], v[150:151]
	v_pk_mul_f32 v[26:27], v[26:27], v[150:151]
	s_waitcnt lgkmcnt(0)
	v_mfma_f32_16x16x32_bf16 v[12:15], v[72:75], v[76:79], v[12:15]
	ds_read_b64_tr_b16 v[76:77], v84 offset:9216
	ds_read_b64_tr_b16 v[78:79], v84 offset:13824
	ds_read_b64_tr_b16 v[82:83], v84 offset:4640
	v_pk_mul_f32 v[24:25], v[24:25], v[148:149]
	s_waitcnt lgkmcnt(1)
	v_mfma_f32_16x16x32_bf16 v[12:15], v[68:71], v[76:79], v[12:15]
	ds_read_b64_tr_b16 v[76:77], v84 offset:9248
	ds_read_b64_tr_b16 v[78:79], v84 offset:13856
	v_pk_mul_f32 v[34:35], v[34:35], v[150:151]
	v_pk_mul_f32 v[32:33], v[32:33], v[148:149]
	s_waitcnt lgkmcnt(2)
	v_mfma_f32_16x16x32_bf16 v[16:19], v[72:75], v[80:83], v[16:19]
	v_mul_f32_e64 v22, v22, v150
	v_mul_f32_e64 v23, v23, v151
	v_pk_mul_f32 v[20:21], v[20:21], v[148:149]
	v_pk_mul_f32 v[30:31], v[30:31], v[150:151]
	s_waitcnt lgkmcnt(0)
	v_mfma_f32_16x16x32_bf16 v[16:19], v[68:71], v[76:79], v[16:19]
	ds_read_b64_tr_b16 v[76:77], v84 offset:64
	ds_read_b64_tr_b16 v[78:79], v84 offset:4672
	ds_read_b64_tr_b16 v[228:229], v84 offset:9280
	ds_read_b64_tr_b16 v[230:231], v84 offset:13888
	ds_read_b64_tr_b16 v[232:233], v84 offset:96
	ds_read_b64_tr_b16 v[234:235], v84 offset:4704
	ds_read_b64_tr_b16 v[236:237], v84 offset:9312
	ds_read_b64_tr_b16 v[238:239], v84 offset:13920
	v_pk_mul_f32 v[28:29], v[28:29], v[148:149]
	v_pk_mul_f32 v[38:39], v[38:39], v[150:151]
	s_waitcnt lgkmcnt(6)
	v_mfma_f32_16x16x32_bf16 v[24:27], v[72:75], v[76:79], v[24:27]
	ds_read_b64_tr_b16 v[76:77], v84 offset:128
	ds_read_b64_tr_b16 v[78:79], v84 offset:4736
	v_pk_mul_f32 v[36:37], v[36:37], v[148:149]
	v_pk_mul_f32 v[42:43], v[42:43], v[150:151]
	s_waitcnt lgkmcnt(6)
	v_mfma_f32_16x16x32_bf16 v[24:27], v[68:71], v[228:231], v[24:27]
	ds_read_b64_tr_b16 v[228:229], v84 offset:9344
	ds_read_b64_tr_b16 v[230:231], v84 offset:13952
	v_pk_mul_f32 v[40:41], v[40:41], v[148:149]
	v_lshlrev_b32_e32 v95, 4, v187
	s_waitcnt lgkmcnt(6)
	v_mfma_f32_16x16x32_bf16 v[32:35], v[72:75], v[232:235], v[32:35]
	ds_read_b64_tr_b16 v[232:233], v84 offset:160
	ds_read_b64_tr_b16 v[234:235], v84 offset:4768
	v_add_u32_e32 v89, s84, v95
	v_add_u32_e32 v90, v89, v185
	s_waitcnt lgkmcnt(6)
	v_mfma_f32_16x16x32_bf16 v[32:35], v[68:71], v[236:239], v[32:35]
	ds_read_b64_tr_b16 v[236:237], v84 offset:9376
	ds_read_b64_tr_b16 v[238:239], v84 offset:13984
	s_waitcnt lgkmcnt(6)
	v_mfma_f32_16x16x32_bf16 v[20:23], v[72:75], v[76:79], v[20:23]
	ds_read_b64_tr_b16 v[76:77], v84 offset:192
	ds_read_b64_tr_b16 v[78:79], v84 offset:4800
	s_waitcnt lgkmcnt(6)
	v_mfma_f32_16x16x32_bf16 v[20:23], v[68:71], v[228:231], v[20:23]
	ds_read_b64_tr_b16 v[228:229], v84 offset:9408
	ds_read_b64_tr_b16 v[230:231], v84 offset:14016
	s_waitcnt lgkmcnt(6)
	v_mfma_f32_16x16x32_bf16 v[28:31], v[72:75], v[232:235], v[28:31]
	ds_read_b64_tr_b16 v[232:233], v84 offset:224
	ds_read_b64_tr_b16 v[234:235], v84 offset:4832
	s_waitcnt lgkmcnt(6)
	v_mfma_f32_16x16x32_bf16 v[28:31], v[68:71], v[236:239], v[28:31]
	s_waitcnt lgkmcnt(4)
	v_mfma_f32_16x16x32_bf16 v[36:39], v[72:75], v[76:79], v[36:39]
	s_waitcnt lgkmcnt(2)
	v_mfma_f32_16x16x32_bf16 v[36:39], v[68:71], v[228:231], v[36:39]
	s_waitcnt lgkmcnt(0)
	v_mfma_f32_16x16x32_bf16 v[40:43], v[72:75], v[232:235], v[40:43]
	ds_read_b64_tr_b16 v[72:73], v84 offset:9440
	ds_read_b64_tr_b16 v[74:75], v84 offset:14048
	s_waitcnt lgkmcnt(0)
	v_mfma_f32_16x16x32_bf16 v[40:43], v[68:71], v[72:75], v[40:43]
	v_add_u32_e32 v68, s85, v128
	v_mul_lo_u32 v68, v68, s61
	v_add_u32_e32 v68, 0, v68
	v_add_u32_e32 v88, v68, v95
	ds_read_b128 v[80:83], v88 offset:17408
	ds_read_b128 v[84:87], v88 offset:17472
	ds_read_b128 v[96:99], v88 offset:17536
	ds_read_b128 v[132:135], v88 offset:17600
	ds_read_b128 v[68:71], v90
	ds_read_b128 v[72:75], v90 offset:64
	ds_read_b128 v[76:79], v90 offset:128
	ds_read_b128 v[136:139], v90 offset:192
	s_waitcnt lgkmcnt(3)
	v_mfma_f32_16x16x32_bf16 v[68:71], v[68:71], v[80:83], 0
	v_add_u32_e32 v90, v89, v129
	s_waitcnt lgkmcnt(2)
	v_mfma_f32_16x16x32_bf16 v[68:71], v[72:75], v[84:87], v[68:71]
	s_waitcnt lgkmcnt(1)
	v_mfma_f32_16x16x32_bf16 v[68:71], v[76:79], v[96:99], v[68:71]
	s_waitcnt lgkmcnt(0)
	v_mfma_f32_16x16x32_bf16 v[68:71], v[136:139], v[132:135], v[68:71]
	ds_read_b128 v[72:75], v90
	ds_read_b128 v[76:79], v90 offset:64
	ds_read_b128 v[136:139], v90 offset:128
	ds_read_b128 v[140:143], v90 offset:192
	v_add_u32_e32 v90, v89, v186
	v_add_u32_e32 v89, v89, v131
	s_waitcnt lgkmcnt(3)
	v_mfma_f32_16x16x32_bf16 v[72:75], v[72:75], v[80:83], 0
	s_waitcnt lgkmcnt(2)
	v_mfma_f32_16x16x32_bf16 v[72:75], v[76:79], v[84:87], v[72:75]
	s_waitcnt lgkmcnt(1)
	v_mfma_f32_16x16x32_bf16 v[72:75], v[136:139], v[96:99], v[72:75]
	s_waitcnt lgkmcnt(0)
	v_mfma_f32_16x16x32_bf16 v[72:75], v[140:143], v[132:135], v[72:75]
	ds_read_b128 v[76:79], v90
	ds_read_b128 v[136:139], v90 offset:64
	ds_read_b128 v[140:143], v90 offset:128
	ds_read_b128 v[144:147], v90 offset:192
	s_waitcnt lgkmcnt(3)
	v_mfma_f32_16x16x32_bf16 v[76:79], v[76:79], v[80:83], 0
	s_waitcnt lgkmcnt(2)
	v_mfma_f32_16x16x32_bf16 v[76:79], v[136:139], v[84:87], v[76:79]
	s_waitcnt lgkmcnt(1)
	v_mfma_f32_16x16x32_bf16 v[76:79], v[140:143], v[96:99], v[76:79]
	s_waitcnt lgkmcnt(0)
	v_mfma_f32_16x16x32_bf16 v[76:79], v[144:147], v[132:135], v[76:79]
	ds_read_b128 v[136:139], v89
	ds_read_b128 v[140:143], v89 offset:64
	ds_read_b128 v[144:147], v89 offset:128
	ds_read_b128 v[148:151], v89 offset:192
	s_waitcnt lgkmcnt(3)
	v_mfma_f32_16x16x32_bf16 v[80:83], v[136:139], v[80:83], 0
	s_waitcnt lgkmcnt(2)
	v_mfma_f32_16x16x32_bf16 v[80:83], v[140:143], v[84:87], v[80:83]
	v_cndmask_b32_e64 v84, 0, 1, s[34:35]
	v_or_b32_e32 v85, 2, v130
	v_cmp_ne_u32_e64 s[0:1], 1, v84
	s_waitcnt lgkmcnt(1)
	v_mfma_f32_16x16x32_bf16 v[80:83], v[144:147], v[96:99], v[80:83]
	v_cmp_le_i32_e64 s[36:37], v85, v128
	s_waitcnt lgkmcnt(0)
	v_mfma_f32_16x16x32_bf16 v[80:83], v[148:151], v[132:135], v[80:83]
	s_cbranch_vccnz .LBB0_608
	s_and_b64 s[30:31], s[38:39], s[36:37]
	s_andn2_b64 s[36:37], s[18:19], exec
	s_and_b64 s[30:31], s[30:31], exec
	s_or_b64 s[30:31], s[36:37], s[30:31]
